# GEMM1 k-loops: next k-step's 8 A fragments read inside the wave's own MFMA segment (after each fragment's last MFMA); data segment reads only the 4 B fragments; one DMA stage in flight across the clos
# baseline (speedup 1.0000x reference)
.LBB0_127:
	s_add_i32 s0, s7, 1
	s_cmp_lg_u32 s7, 3
	s_waitcnt lgkmcnt(0)
	v_mfma_f32_16x16x32_bf16 v[124:127], v[148:151], v[172:175], v[124:127]
	s_cselect_b32 s7, s0, 0
	s_lshl_b32 s11, s7, 15
	s_add_i32 s10, s10, 1
	s_waitcnt lgkmcnt(0)
	v_mfma_f32_16x16x32_bf16 v[120:123], v[144:147], v[172:175], v[120:123]
	s_add_u32 s2, s2, 64
	s_addc_u32 s3, s3, 0
	s_cmpk_lg_i32 s2, 0x800
	v_mfma_f32_16x16x32_bf16 v[116:119], v[136:139], v[172:175], v[116:119]
	s_barrier
	v_or_b32_e32 v222, s11, v211
	v_add3_u32 v222, v222, s20, v212
	v_mfma_f32_16x16x32_bf16 v[112:115], v[132:135], v[172:175], v[112:115]
	ds_read_b128 v[172:175], v222
	v_mfma_f32_16x16x32_bf16 v[108:111], v[148:151], v[168:171], v[108:111]
	v_mfma_f32_16x16x32_bf16 v[104:107], v[144:147], v[168:171], v[104:107]
	v_mfma_f32_16x16x32_bf16 v[100:103], v[136:139], v[168:171], v[100:103]
	v_mfma_f32_16x16x32_bf16 v[96:99], v[132:135], v[168:171], v[96:99]
	ds_read_b128 v[168:171], v222 offset:1024
	v_mfma_f32_16x16x32_bf16 v[92:95], v[148:151], v[164:167], v[92:95]
	v_mfma_f32_16x16x32_bf16 v[88:91], v[144:147], v[164:167], v[88:91]
	v_mfma_f32_16x16x32_bf16 v[84:87], v[136:139], v[164:167], v[84:87]
	v_mfma_f32_16x16x32_bf16 v[80:83], v[132:135], v[164:167], v[80:83]
	ds_read_b128 v[164:167], v222 offset:2048
	v_mfma_f32_16x16x32_bf16 v[76:79], v[148:151], v[160:163], v[76:79]
	v_mfma_f32_16x16x32_bf16 v[72:75], v[144:147], v[160:163], v[72:75]
	v_mfma_f32_16x16x32_bf16 v[68:71], v[136:139], v[160:163], v[68:71]
	v_mfma_f32_16x16x32_bf16 v[64:67], v[132:135], v[160:163], v[64:67]
	ds_read_b128 v[160:163], v222 offset:3072
	v_mfma_f32_16x16x32_bf16 v[60:63], v[148:151], v[156:159], v[60:63]
	v_mfma_f32_16x16x32_bf16 v[56:59], v[144:147], v[156:159], v[56:59]
	v_mfma_f32_16x16x32_bf16 v[52:55], v[136:139], v[156:159], v[52:55]
	v_mfma_f32_16x16x32_bf16 v[48:51], v[132:135], v[156:159], v[48:51]
	ds_read_b128 v[156:159], v222 offset:4096
	v_mfma_f32_16x16x32_bf16 v[44:47], v[148:151], v[152:155], v[44:47]
	v_mfma_f32_16x16x32_bf16 v[40:43], v[144:147], v[152:155], v[40:43]
	v_mfma_f32_16x16x32_bf16 v[36:39], v[136:139], v[152:155], v[36:39]
	v_mfma_f32_16x16x32_bf16 v[32:35], v[132:135], v[152:155], v[32:35]
	ds_read_b128 v[152:155], v222 offset:5120
	v_mfma_f32_16x16x32_bf16 v[28:31], v[148:151], v[140:143], v[28:31]
	v_mfma_f32_16x16x32_bf16 v[24:27], v[144:147], v[140:143], v[24:27]
	v_mfma_f32_16x16x32_bf16 v[20:23], v[136:139], v[140:143], v[20:23]
	v_mfma_f32_16x16x32_bf16 v[16:19], v[132:135], v[140:143], v[16:19]
	ds_read_b128 v[140:143], v222 offset:6144
	v_mfma_f32_16x16x32_bf16 v[12:15], v[148:151], v[128:131], v[12:15]
	v_mfma_f32_16x16x32_bf16 v[8:11], v[144:147], v[128:131], v[8:11]
	v_mfma_f32_16x16x32_bf16 v[4:7], v[136:139], v[128:131], v[4:7]
	v_mfma_f32_16x16x32_bf16 v[0:3], v[132:135], v[128:131], v[0:3]
	ds_read_b128 v[128:131], v222 offset:7168
	s_cbranch_scc0 .LBB0_132
.LBB0_128:
	s_lshl_b32 s11, s7, 15
	v_or_b32_e32 v132, s11, v211
	s_barrier
	s_cmp_lg_u32 s10, 0
	s_cbranch_scc1 .Lapf_b1
	v_add3_u32 v128, v132, s20, v212
	ds_read_b128 v[172:175], v128
	ds_read_b128 v[168:171], v128 offset:1024
	ds_read_b128 v[164:167], v128 offset:2048
	ds_read_b128 v[160:163], v128 offset:3072
	ds_read_b128 v[156:159], v128 offset:4096
	ds_read_b128 v[152:155], v128 offset:5120
	ds_read_b128 v[140:143], v128 offset:6144
	ds_read_b128 v[128:131], v128 offset:7168
.Lapf_b1:
	v_add3_u32 v132, v132, s40, v212
	ds_read_b128 v[148:151], v132 offset:16384
	ds_read_b128 v[144:147], v132 offset:17408
	ds_read_b128 v[136:139], v132 offset:18432
	ds_read_b128 v[132:135], v132 offset:19456
	s_cmp_lt_u32 s10, 29
	s_cselect_b64 s[0:1], -1, 0
	s_or_b64 s[12:13], s[8:9], s[0:1]
	s_cbranch_scc1 .Lgk_i1
	s_waitcnt vmcnt(0)
	s_branch .LBB0_127

.Lgp_1:
	s_addk_i32 s11, 0x8000
	s_cmp_gt_i32 s7, 0
	s_cselect_b32 s0, s11, 0x18000
	s_add_i32 s0, s15, s0
	s_add_i32 s12, s0, 0x4000
	s_mov_b32 m0, s0
	s_add_i32 s11, s0, 0x2000
	global_load_lds_dwordx4 v[198:199], off
	s_mov_b32 m0, s12
	s_add_i32 s1, s0, 0x6000
	v_lshl_add_u64 v[224:225], v[198:199], 0, s[94:95]
	global_load_lds_dwordx4 v[200:201], off
	s_mov_b32 m0, s11
	v_lshl_add_u64 v[222:223], v[200:201], 0, s[94:95]
	global_load_lds_dwordx4 v[224:225], off
	s_mov_b32 m0, s1
	v_lshl_add_u64 v[198:199], v[198:199], 0, 64
	global_load_lds_dwordx4 v[222:223], off
	v_lshl_add_u64 v[200:201], v[200:201], 0, 64
	s_waitcnt vmcnt(4)
	s_branch .LBB0_127
.LBB0_132:
	s_waitcnt lgkmcnt(0)
	s_mov_b64 s[0:1], 0

.LBB0_136:
	s_lshl_b32 s10, s52, 15
	v_or_b32_e32 v132, s10, v211
	v_add_u32_e32 v132, v132, v212
	s_cmp_lg_u32 s7, 0
	s_cbranch_scc1 .Lapf_b2
	ds_read_b128 v[172:175], v132
	ds_read_b128 v[168:171], v132 offset:1024
	ds_read_b128 v[164:167], v132 offset:2048
	ds_read_b128 v[160:163], v132 offset:3072
	ds_read_b128 v[156:159], v132 offset:4096
	ds_read_b128 v[152:155], v132 offset:5120
	ds_read_b128 v[136:139], v132 offset:6144
	ds_read_b128 v[128:131], v132 offset:7168
.Lapf_b2:
	v_add_u32_e32 v132, s41, v132
	ds_read_b128 v[144:147], v132 offset:16384
	ds_read_b128 v[148:151], v132 offset:17408
	ds_read_b128 v[140:143], v132 offset:18432
	ds_read_b128 v[132:135], v132 offset:19456
	s_cmp_lt_u32 s7, 29
	s_cselect_b64 s[0:1], -1, 0
	s_nor_b64 s[12:13], s[8:9], s[0:1]
	s_cbranch_scc1 .LBB0_138
	s_cmp_lg_u32 s7, 29
	s_cbranch_scc1 .Lgp_2
	v_lshl_add_u64 v[188:189], v[192:193], 0, s[2:3]
	v_lshl_add_u64 v[186:187], v[190:191], 0, s[2:3]

.LBB0_138:
	s_waitcnt lgkmcnt(0)
	v_mfma_f32_16x16x32_bf16 v[124:127], v[144:147], v[172:175], v[124:127]
	s_waitcnt lgkmcnt(0)
	v_mfma_f32_16x16x32_bf16 v[120:123], v[148:151], v[172:175], v[120:123]
	s_barrier
	s_add_i32 s10, s52, 1
	s_and_b32 s10, s10, 3
	s_lshl_b32 s10, s10, 15
	v_or_b32_e32 v198, s10, v211
	v_add_u32_e32 v198, v198, v212
	v_mfma_f32_16x16x32_bf16 v[116:119], v[140:143], v[172:175], v[116:119]
	v_mfma_f32_16x16x32_bf16 v[112:115], v[132:135], v[172:175], v[112:115]
	ds_read_b128 v[172:175], v198
	v_mfma_f32_16x16x32_bf16 v[108:111], v[144:147], v[168:171], v[108:111]
	v_mfma_f32_16x16x32_bf16 v[104:107], v[148:151], v[168:171], v[104:107]
	v_mfma_f32_16x16x32_bf16 v[100:103], v[140:143], v[168:171], v[100:103]
	v_mfma_f32_16x16x32_bf16 v[96:99], v[132:135], v[168:171], v[96:99]
	ds_read_b128 v[168:171], v198 offset:1024
	v_mfma_f32_16x16x32_bf16 v[92:95], v[144:147], v[164:167], v[92:95]
	v_mfma_f32_16x16x32_bf16 v[88:91], v[148:151], v[164:167], v[88:91]
	v_mfma_f32_16x16x32_bf16 v[84:87], v[140:143], v[164:167], v[84:87]
	v_mfma_f32_16x16x32_bf16 v[80:83], v[132:135], v[164:167], v[80:83]
	ds_read_b128 v[164:167], v198 offset:2048
	v_mfma_f32_16x16x32_bf16 v[76:79], v[144:147], v[160:163], v[76:79]
	v_mfma_f32_16x16x32_bf16 v[72:75], v[148:151], v[160:163], v[72:75]
	v_mfma_f32_16x16x32_bf16 v[68:71], v[140:143], v[160:163], v[68:71]
	v_mfma_f32_16x16x32_bf16 v[64:67], v[132:135], v[160:163], v[64:67]
	ds_read_b128 v[160:163], v198 offset:3072
	v_mfma_f32_16x16x32_bf16 v[60:63], v[144:147], v[156:159], v[60:63]
	v_mfma_f32_16x16x32_bf16 v[56:59], v[148:151], v[156:159], v[56:59]
	v_mfma_f32_16x16x32_bf16 v[52:55], v[140:143], v[156:159], v[52:55]
	v_mfma_f32_16x16x32_bf16 v[48:51], v[132:135], v[156:159], v[48:51]
	ds_read_b128 v[156:159], v198 offset:4096
	v_mfma_f32_16x16x32_bf16 v[44:47], v[144:147], v[152:155], v[44:47]
	v_mfma_f32_16x16x32_bf16 v[40:43], v[148:151], v[152:155], v[40:43]
	v_mfma_f32_16x16x32_bf16 v[36:39], v[140:143], v[152:155], v[36:39]
	v_mfma_f32_16x16x32_bf16 v[32:35], v[132:135], v[152:155], v[32:35]
	ds_read_b128 v[152:155], v198 offset:5120
	v_mfma_f32_16x16x32_bf16 v[28:31], v[144:147], v[136:139], v[28:31]
	v_mfma_f32_16x16x32_bf16 v[24:27], v[148:151], v[136:139], v[24:27]
	v_mfma_f32_16x16x32_bf16 v[20:23], v[140:143], v[136:139], v[20:23]
	v_mfma_f32_16x16x32_bf16 v[16:19], v[132:135], v[136:139], v[16:19]
	ds_read_b128 v[136:139], v198 offset:6144
	v_mfma_f32_16x16x32_bf16 v[12:15], v[144:147], v[128:131], v[12:15]
	v_mfma_f32_16x16x32_bf16 v[8:11], v[148:151], v[128:131], v[8:11]
	v_mfma_f32_16x16x32_bf16 v[4:7], v[140:143], v[128:131], v[4:7]
	v_mfma_f32_16x16x32_bf16 v[0:3], v[132:135], v[128:131], v[0:3]
	ds_read_b128 v[128:131], v198 offset:7168
	s_cmp_lg_u64 s[12:13], 0
	s_cbranch_scc1 .Lgk_w1
	s_waitcnt vmcnt(4)
	s_branch .LBB0_135

.LBB0_142:
	s_waitcnt lgkmcnt(0)
	s_mov_b32 s7, s52
